# attention phase: static s_setprio 1 for waves 4-7 (reset at phase end)
# baseline (speedup 1.0000x reference)
.LBB0_1295:
	s_or_b64 exec, exec, s[0:1]
	s_mov_b64 s[0:1], s[66:67]
	s_mov_b64 s[6:7], s[68:69]
	s_waitcnt lgkmcnt(0)
	s_barrier
	v_readfirstlane_b32 s98, v194
	s_lshr_b32 s98, s98, 6
	s_cmp_ge_u32 s98, 4
	s_cbranch_scc0 .Laprio_0
	s_setprio 1
.Laprio_0:
	v_mov_b32_e32 v0, v194
	s_mov_b32 s42, s64
	s_and_b32 s6, s42, 7
	s_mov_b32 s43, 0
	s_cmp_lg_u32 s6, 0
	s_mov_b32 s44, s2
	s_cbranch_scc1 .LBB0_1297
	s_lshr_b32 s7, s3, 29
	s_add_i32 s7, s2, s7
	s_and_b32 s14, s7, -8
	s_ashr_i32 s6, s42, 3
	s_sub_i32 s14, s2, s14
	s_mul_i32 s6, s6, s14
	s_ashr_i32 s7, s7, 3
	s_add_i32 s44, s6, s7

.LBB0_1350:
	s_setprio 0
	s_getreg_b32 s6, hwreg(HW_REG_XCC_ID, 0, 4)
	s_waitcnt vmcnt(0)
	s_barrier
	s_and_saveexec_b64 s[0:1], s[46:47]
	s_cbranch_execz .LBB0_1402
	s_add_i32 s7, 0, 0x20160
	v_mov_b32_e32 v0, s7
	s_waitcnt vmcnt(0) expcnt(0) lgkmcnt(0)
	ds_read_b32 v2, v0
	s_add_i32 s7, 0, 0x20164
	v_mov_b32_e32 v0, s7
	ds_read_b32 v0, v0
	s_and_b32 s51, s6, 15
	s_waitcnt lgkmcnt(1)
	v_cmp_ne_u32_e32 vcc, 0, v2
	s_cbranch_vccnz .LBB0_1366
	s_add_u32 s6, s66, 0x1200
	s_addc_u32 s7, s67, 0
	s_add_u32 s14, s66, 0x1400
	s_addc_u32 s15, s67, 0
	s_add_u32 s16, s66, 0x1500
	s_addc_u32 s17, s67, 0
	s_add_u32 s18, s66, 0x1600
	s_addc_u32 s19, s67, 0
	s_add_u32 s20, s66, 0x1700
	s_addc_u32 s21, s67, 0
	s_add_u32 s22, s66, 0x1800
	s_addc_u32 s23, s67, 0
	s_add_u32 s24, s66, 0x1900
	s_addc_u32 s25, s67, 0
	s_add_u32 s26, s66, 0x1a00
	s_addc_u32 s27, s67, 0
	s_add_u32 s28, s66, 0x1b00
	s_addc_u32 s29, s67, 0
	s_add_u32 s30, s66, 0x1c00
	s_addc_u32 s31, s67, 0
	s_add_u32 s34, s66, 0x1d00
	s_addc_u32 s35, s67, 0
	s_add_u32 s36, s66, 0x1e00
	s_addc_u32 s37, s67, 0
	s_add_u32 s38, s66, 0x1f00
	s_addc_u32 s39, s67, 0
	s_add_u32 s40, s66, 0x2000
	s_addc_u32 s41, s67, 0
	s_add_u32 s42, s66, 0x2100
	s_addc_u32 s43, s67, 0
	s_add_u32 s44, s66, 0x2200
	s_addc_u32 s45, s67, 0
	s_mul_i32 s72, s65, s74
	s_add_u32 s58, s66, 0x2300
	s_mul_i32 s72, s72, s64
	s_addc_u32 s59, s67, 0
	s_mov_b32 s73, 1
	v_mov_b32_e32 v16, 0
	s_branch .LBB0_1354

.LBB0_2905:
	s_or_b64 exec, exec, s[0:1]
	s_mov_b64 s[0:1], s[66:67]
	s_mov_b64 s[8:9], s[68:69]
	s_waitcnt lgkmcnt(0)
	s_barrier
	v_readfirstlane_b32 s98, v194
	s_lshr_b32 s98, s98, 6
	s_cmp_ge_u32 s98, 4
	s_cbranch_scc0 .Laprio_1
	s_setprio 1
.Laprio_1:
	v_mov_b32_e32 v0, v194
	s_mov_b32 s38, s64
	s_and_b32 s8, s38, 7
	s_mov_b32 s39, 0
	s_cmp_lg_u32 s8, 0
	s_mov_b32 s40, s2
	s_cbranch_scc1 .LBB0_2907
	s_lshr_b32 s9, s3, 29
	s_add_i32 s9, s2, s9
	s_and_b32 s10, s9, -8
	s_ashr_i32 s8, s38, 3
	s_sub_i32 s10, s2, s10
	s_mul_i32 s8, s8, s10
	s_ashr_i32 s9, s9, 3
	s_add_i32 s40, s8, s9

.LBB0_2960:
	s_setprio 0
	s_getreg_b32 s8, hwreg(HW_REG_XCC_ID, 0, 4)
	s_waitcnt vmcnt(0)
	s_barrier
	s_and_saveexec_b64 s[0:1], s[46:47]
	s_cbranch_execz .LBB0_3012
	s_add_i32 s9, 0, 0x20160
	v_mov_b32_e32 v0, s9
	s_waitcnt vmcnt(0) expcnt(0) lgkmcnt(0)
	ds_read_b32 v2, v0
	s_add_i32 s9, 0, 0x20164
	v_mov_b32_e32 v0, s9
	ds_read_b32 v0, v0
	s_and_b32 s52, s8, 15
	s_waitcnt lgkmcnt(1)
	v_cmp_ne_u32_e32 vcc, 0, v2
	s_cbranch_vccnz .LBB0_2976
	s_add_u32 s8, s66, 0x1200
	s_addc_u32 s9, s67, 0
	s_add_u32 s10, s66, 0x1400
	s_addc_u32 s11, s67, 0
	s_add_u32 s12, s66, 0x1500
	s_addc_u32 s13, s67, 0
	s_add_u32 s14, s66, 0x1600
	s_addc_u32 s15, s67, 0
	s_add_u32 s16, s66, 0x1700
	s_addc_u32 s17, s67, 0
	s_add_u32 s18, s66, 0x1800
	s_addc_u32 s19, s67, 0
	s_add_u32 s20, s66, 0x1900
	s_addc_u32 s21, s67, 0
	s_add_u32 s22, s66, 0x1a00
	s_addc_u32 s23, s67, 0
	s_add_u32 s24, s66, 0x1b00
	s_addc_u32 s25, s67, 0
	s_add_u32 s26, s66, 0x1c00
	s_addc_u32 s27, s67, 0
	s_add_u32 s28, s66, 0x1d00
	s_addc_u32 s29, s67, 0
	s_add_u32 s30, s66, 0x1e00
	s_addc_u32 s31, s67, 0
	s_add_u32 s34, s66, 0x1f00
	s_addc_u32 s35, s67, 0
	s_add_u32 s36, s66, 0x2000
	s_addc_u32 s37, s67, 0
	s_add_u32 s38, s66, 0x2100
	s_addc_u32 s39, s67, 0
	s_add_u32 s40, s66, 0x2200
	s_addc_u32 s41, s67, 0
	s_mul_i32 s53, s65, s74
	s_add_u32 s42, s66, 0x2300
	s_mul_i32 s53, s53, s64
	s_addc_u32 s43, s67, 0
	s_mov_b32 s54, 1
	v_mov_b32_e32 v16, 0
	s_branch .LBB0_2964
